# NSA selected/window loops: later K and V^T fragment reads of each tile hoisted into registers unused in those loops (v[238:249]), counted lgkmcnt waits instead of read-wait-MFMA ladders
# speedup vs baseline: 1.0018x; 1.0018x over previous
.LBB0_351:
	v_lshrrev_b64 v[66:67], s24, v[110:111]
	v_and_b32_e32 v0, 1, v66
	v_cmp_eq_u32_e32 vcc, 1, v0
	s_mul_i32 s8, s19, 0x4800
	s_add_i32 s25, s8, 0
	v_cndmask_b32_e32 v88, -1, v192, vcc
	v_cmp_lt_i32_e64 s[10:11], -1, v88
	s_cmp_eq_u64 s[10:11], 0
	s_cselect_b64 s[20:21], -1, 0
	s_lshl_b32 s27, s24, 6
	s_cmp_gt_i32 s27, s61
	v_add_u32_e32 v0, s25, v170
	v_add_u32_e32 v86, s25, v171
	s_cselect_b64 s[24:25], -1, 0
	s_or_b64 s[24:25], s[20:21], s[24:25]
	v_cmp_gt_i32_e64 s[8:9], 0, v88
	s_and_b64 vcc, exec, s[24:25]
	v_add_u32_e32 v90, v0, v204
	s_cbranch_vccnz .LBB0_359
	ds_read_b128 v[66:69], v90
	ds_read_b128 v[92:95], v90 offset:32
	ds_read_b128 v[238:241], v90 offset:64
	ds_read_b128 v[242:245], v90 offset:96
	s_or_b32 s24, s27, 31
	s_cmp_le_i32 s24, s91
	s_mov_b64 s[24:25], -1
	s_waitcnt lgkmcnt(2)
	v_mfma_f32_32x32x16_bf16 v[66:81], v[66:69], v[114:117], 0
	v_mfma_f32_32x32x16_bf16 v[66:81], v[92:95], v[118:121], v[66:81]
	s_waitcnt lgkmcnt(1)
	v_mfma_f32_32x32x16_bf16 v[66:81], v[238:241], v[126:129], v[66:81]
	s_waitcnt lgkmcnt(0)
	v_mfma_f32_32x32x16_bf16 v[66:81], v[242:245], v[122:125], v[66:81]
	s_cbranch_scc0 .LBB0_369
	s_nop 10
	v_max3_f32 v0, v66, s72, v67
	v_max3_f32 v0, v0, v68, v69
	v_max3_f32 v0, v0, v70, v71
	v_max3_f32 v0, v0, v72, v73
	v_max3_f32 v0, v0, v74, v75
	v_max3_f32 v0, v0, v76, v77
	v_max3_f32 v0, v0, v78, v79
	v_mov_b32_e32 v89, v222
	v_max3_f32 v0, v0, v80, v81
	v_mul_f32_e32 v0, 0x3e38aa3b, v0
	v_lshlrev_b32_e32 v89, 2, v89
	v_cndmask_b32_e64 v0, v230, v0, s[10:11]
	v_xor_b32_e32 v89, 0x80, v89
	ds_bpermute_b32 v89, v89, v0
	s_waitcnt lgkmcnt(0)
	v_max3_f32 v89, v87, v0, v89
	v_cndmask_b32_e64 v221, -v230, v89, s[10:11]
	v_fma_f32 v0, v66, s36, -v221
	v_exp_f32_e32 v91, v0
	v_fma_f32 v0, v67, s36, -v221
	v_exp_f32_e32 v92, v0
	v_fma_f32 v0, v68, s36, -v221
	v_exp_f32_e32 v95, v0
	v_fma_f32 v0, v69, s36, -v221
	v_exp_f32_e32 v94, v0
	v_fma_f32 v93, v70, s36, -v221
	v_add_f32_e32 v0, 0, v91
	v_exp_f32_e32 v97, v93
	v_fma_f32 v93, v71, s36, -v221
	v_add_f32_e32 v0, v92, v0
	v_exp_f32_e32 v96, v93
	v_fma_f32 v93, v72, s36, -v221
	v_add_f32_e32 v0, v95, v0
	v_exp_f32_e32 v99, v93
	v_fma_f32 v93, v73, s36, -v221
	v_add_f32_e32 v0, v94, v0
	v_exp_f32_e32 v98, v93
	v_fma_f32 v93, v74, s36, -v221
	v_add_f32_e32 v0, v97, v0
	v_exp_f32_e32 v101, v93
	v_fma_f32 v93, v75, s36, -v221
	v_add_f32_e32 v0, v96, v0
	v_exp_f32_e32 v100, v93
	v_fma_f32 v93, v76, s36, -v221
	v_add_f32_e32 v0, v99, v0
	v_exp_f32_e32 v103, v93
	v_fma_f32 v93, v77, s36, -v221
	v_add_f32_e32 v0, v98, v0
	v_exp_f32_e32 v102, v93
	v_fma_f32 v93, v78, s36, -v221
	v_add_f32_e32 v0, v101, v0
	v_exp_f32_e32 v105, v93
	v_fma_f32 v93, v79, s36, -v221
	v_add_f32_e32 v0, v100, v0
	v_exp_f32_e32 v104, v93
	v_fma_f32 v93, v80, s36, -v221
	v_add_f32_e32 v0, v103, v0
	v_exp_f32_e32 v107, v93
	v_fma_f32 v93, v81, s36, -v221
	v_add_f32_e32 v0, v102, v0
	v_exp_f32_e32 v106, v93
	v_add_f32_e32 v0, v105, v0
	v_add_f32_e32 v0, v104, v0
	v_add_f32_e32 v0, v107, v0
	v_add_f32_e32 v93, v106, v0
	v_sub_f32_e32 v0, v87, v89
	v_exp_f32_e32 v0, v0
	s_cbranch_execz .LBB0_370

.LBB0_358:
	s_nop 1
	v_add_u32_e32 v78, v86, v170
	s_nop 3
	ds_read_b128 v[66:69], v78 offset:9216
	ds_read_b128 v[238:241], v78 offset:9248
	ds_read_b128 v[242:245], v78 offset:13824
	ds_read_b128 v[246:249], v78 offset:13856
	v_cvt_pk_bf16_f32 v70, v91, v92
	v_cvt_pk_bf16_f32 v71, v95, v94
	v_cvt_pk_bf16_f32 v72, v97, v96
	v_cvt_pk_bf16_f32 v73, v99, v98
	v_cvt_pk_bf16_f32 v74, v101, v100
	v_cvt_pk_bf16_f32 v75, v103, v102
	v_cvt_pk_bf16_f32 v76, v105, v104
	v_cvt_pk_bf16_f32 v77, v107, v106
	s_waitcnt lgkmcnt(3)
	v_mfma_f32_32x32x16_bf16 v[34:49], v[66:69], v[70:73], v[34:49]
	v_fmac_f32_e32 v93, v146, v0
	v_mov_b32_e32 v146, v93
	s_waitcnt lgkmcnt(2)
	v_mfma_f32_32x32x16_bf16 v[34:49], v[238:241], v[74:77], v[34:49]
	s_waitcnt lgkmcnt(1)
	v_mfma_f32_32x32x16_bf16 v[50:65], v[242:245], v[70:73], v[50:65]
	s_waitcnt lgkmcnt(0)
	v_mfma_f32_32x32x16_bf16 v[50:65], v[246:249], v[74:77], v[50:65]
	s_branch .LBB0_360

.LBB0_360:
	s_or_b32 s24, s27, 32
	s_cmp_gt_i32 s24, s61
	s_cselect_b64 s[28:29], -1, 0
	s_or_b64 s[20:21], s[20:21], s[28:29]
	s_and_b64 vcc, exec, s[20:21]
	s_cbranch_vccnz .LBB0_346
	ds_read_b128 v[66:69], v90 offset:4608
	ds_read_b128 v[92:95], v90 offset:4640
	ds_read_b128 v[238:241], v90 offset:4672
	ds_read_b128 v[242:245], v90 offset:4704
	s_or_b32 s20, s27, 63
	s_cmp_gt_i32 s20, s91
	s_mov_b64 s[20:21], -1
	s_waitcnt lgkmcnt(2)
	v_mfma_f32_32x32x16_bf16 v[66:81], v[66:69], v[114:117], 0
	v_mfma_f32_32x32x16_bf16 v[66:81], v[92:95], v[118:121], v[66:81]
	s_waitcnt lgkmcnt(1)
	v_mfma_f32_32x32x16_bf16 v[66:81], v[238:241], v[126:129], v[66:81]
	s_waitcnt lgkmcnt(0)
	v_mfma_f32_32x32x16_bf16 v[66:81], v[242:245], v[122:125], v[66:81]
	s_cbranch_scc1 .LBB0_371
	s_nop 10
	v_max3_f32 v0, v66, s72, v67
	v_max3_f32 v0, v0, v68, v69
	v_max3_f32 v0, v0, v70, v71
	v_max3_f32 v0, v0, v72, v73
	v_max3_f32 v0, v0, v74, v75
	v_max3_f32 v0, v0, v76, v77
	v_max3_f32 v0, v0, v78, v79
	v_mov_b32_e32 v87, v222
	v_max3_f32 v0, v0, v80, v81
	v_mul_f32_e32 v0, 0x3e38aa3b, v0
	v_lshlrev_b32_e32 v87, 2, v87
	v_cndmask_b32_e64 v0, v230, v0, s[10:11]
	v_xor_b32_e32 v87, 0x80, v87
	ds_bpermute_b32 v87, v87, v0
	s_waitcnt lgkmcnt(0)
	v_max3_f32 v87, v89, v0, v87
	v_cndmask_b32_e64 v221, -v230, v87, s[10:11]
	v_fma_f32 v0, v66, s36, -v221
	v_exp_f32_e32 v90, v0
	v_fma_f32 v0, v67, s36, -v221
	v_exp_f32_e32 v91, v0
	v_fma_f32 v0, v68, s36, -v221
	v_exp_f32_e32 v94, v0
	v_fma_f32 v0, v69, s36, -v221
	v_exp_f32_e32 v93, v0
	v_fma_f32 v92, v70, s36, -v221
	v_add_f32_e32 v0, 0, v90
	v_exp_f32_e32 v96, v92
	v_fma_f32 v92, v71, s36, -v221
	v_add_f32_e32 v0, v91, v0
	v_exp_f32_e32 v95, v92
	v_fma_f32 v92, v72, s36, -v221
	v_add_f32_e32 v0, v94, v0
	v_exp_f32_e32 v98, v92
	v_fma_f32 v92, v73, s36, -v221
	v_add_f32_e32 v0, v93, v0
	v_exp_f32_e32 v97, v92
	v_fma_f32 v92, v74, s36, -v221
	v_add_f32_e32 v0, v96, v0
	v_exp_f32_e32 v100, v92
	v_fma_f32 v92, v75, s36, -v221
	v_add_f32_e32 v0, v95, v0
	v_exp_f32_e32 v99, v92
	v_fma_f32 v92, v76, s36, -v221
	v_add_f32_e32 v0, v98, v0
	v_exp_f32_e32 v102, v92
	v_fma_f32 v92, v77, s36, -v221
	v_add_f32_e32 v0, v97, v0
	v_exp_f32_e32 v101, v92
	v_fma_f32 v92, v78, s36, -v221
	v_add_f32_e32 v0, v100, v0
	v_exp_f32_e32 v104, v92
	v_fma_f32 v92, v79, s36, -v221
	v_add_f32_e32 v0, v99, v0
	v_exp_f32_e32 v103, v92
	v_fma_f32 v92, v80, s36, -v221
	v_add_f32_e32 v0, v102, v0
	v_exp_f32_e32 v106, v92
	v_fma_f32 v92, v81, s36, -v221
	v_add_f32_e32 v0, v101, v0
	v_exp_f32_e32 v105, v92
	v_add_f32_e32 v0, v104, v0
	v_add_f32_e32 v0, v103, v0
	v_add_f32_e32 v0, v106, v0
	v_add_f32_e32 v92, v105, v0
	v_sub_f32_e32 v0, v89, v87
	v_exp_f32_e32 v0, v0
	s_cbranch_execz .LBB0_372

.LBB0_367:
	s_nop 6
	v_add_u32_e32 v78, v86, v170
	ds_read_b128 v[66:69], v78 offset:9280
	ds_read_b128 v[238:241], v78 offset:9312
	ds_read_b128 v[242:245], v78 offset:13888
	ds_read_b128 v[246:249], v78 offset:13920
	v_cvt_pk_bf16_f32 v70, v90, v91
	v_cvt_pk_bf16_f32 v71, v94, v93
	v_cvt_pk_bf16_f32 v72, v96, v95
	v_cvt_pk_bf16_f32 v73, v98, v97
	v_cvt_pk_bf16_f32 v74, v100, v99
	v_cvt_pk_bf16_f32 v75, v102, v101
	v_cvt_pk_bf16_f32 v76, v104, v103
	v_cvt_pk_bf16_f32 v77, v106, v105
	s_waitcnt lgkmcnt(3)
	v_mfma_f32_32x32x16_bf16 v[34:49], v[66:69], v[70:73], v[34:49]
	v_fmac_f32_e32 v92, v146, v0
	v_mov_b32_e32 v146, v92
	s_waitcnt lgkmcnt(2)
	v_mfma_f32_32x32x16_bf16 v[34:49], v[238:241], v[74:77], v[34:49]
	s_waitcnt lgkmcnt(1)
	v_mfma_f32_32x32x16_bf16 v[50:65], v[242:245], v[70:73], v[50:65]
	s_waitcnt lgkmcnt(0)
	v_mfma_f32_32x32x16_bf16 v[50:65], v[246:249], v[74:77], v[50:65]
	s_andn2_b64 vcc, exec, s[12:13]
	s_cbranch_vccz .LBB0_347

.LBB0_378:
	s_mul_i32 s0, s24, 0x4800
	s_add_i32 s0, s0, 0
	s_lshl_b32 s26, s8, 6
	v_add_u32_e32 v151, s0, v170
	s_cmp_gt_i32 s26, s61
	v_add_u32_e32 v149, s0, v171
	s_cbranch_scc1 .LBB0_385
	s_or_b32 s0, s26, 31
	s_cmp_lt_i32 s0, s18
	s_cbranch_scc1 .LBB0_385
	v_add_u32_e32 v138, v151, v204
	ds_read_b128 v[98:101], v138
	ds_read_b128 v[196:199], v138 offset:32
	ds_read_b128 v[238:241], v138 offset:64
	ds_read_b128 v[242:245], v138 offset:96
	s_cmp_ge_i32 s26, s19
	s_cselect_b64 s[8:9], -1, 0
	s_cmp_le_i32 s0, s91
	s_cselect_b64 s[0:1], -1, 0
	s_and_b64 s[8:9], s[8:9], s[0:1]
	s_mov_b64 s[0:1], -1
	s_and_b64 vcc, exec, s[8:9]
	s_waitcnt lgkmcnt(2)
	v_mfma_f32_32x32x16_bf16 v[98:113], v[98:101], v[114:117], 0
	v_mfma_f32_32x32x16_bf16 v[98:113], v[196:199], v[118:121], v[98:113]
	s_waitcnt lgkmcnt(1)
	v_mfma_f32_32x32x16_bf16 v[98:113], v[238:241], v[126:129], v[98:113]
	s_waitcnt lgkmcnt(0)
	v_mfma_f32_32x32x16_bf16 v[98:113], v[242:245], v[122:125], v[98:113]
	s_cbranch_vccnz .LBB0_394
	v_or_b32_e32 v138, s26, v202
	v_cmp_ge_i32_e32 vcc, v138, v0
	v_cmp_le_i32_e64 s[0:1], v138, v192
	s_nop 7
	v_mul_f32_e32 v152, 0x3e38aa3b, v98
	s_and_b64 vcc, vcc, s[0:1]
	v_cndmask_b32_e32 v157, v230, v152, vcc
	v_or_b32_e32 v152, 1, v138
	v_cmp_ge_i32_e32 vcc, v152, v0
	v_cmp_lt_i32_e64 s[0:1], v138, v192
	v_mul_f32_e32 v152, 0x3e38aa3b, v99
	s_and_b64 vcc, s[0:1], vcc
	v_cndmask_b32_e32 v167, v230, v152, vcc
	v_mov_b32_e32 v152, v222
	v_or_b32_e32 v153, 2, v138
	v_lshlrev_b32_e32 v152, 2, v152
	v_xor_b32_e32 v193, 0x80, v152
	v_or_b32_e32 v152, 3, v138
	v_cmp_ge_i32_e32 vcc, v152, v141
	v_cmp_le_i32_e64 s[8:9], v152, v139
	v_cmp_ge_i32_e64 s[0:1], v153, v0
	v_cmp_le_i32_e64 s[10:11], v153, v192
	v_pk_mul_f32 v[152:153], v[100:101], s[36:37] op_sel_hi:[1,0]
	s_and_b64 vcc, vcc, s[8:9]
	v_cndmask_b32_e32 v194, v230, v153, vcc
	s_and_b64 vcc, s[0:1], s[10:11]
	v_cndmask_b32_e32 v196, v230, v152, vcc
	v_or_b32_e32 v152, 5, v138
	v_or_b32_e32 v153, 4, v138
	v_cmp_ge_i32_e32 vcc, v152, v141
	v_cmp_le_i32_e64 s[8:9], v152, v139
	v_cmp_ge_i32_e64 s[0:1], v153, v0
	v_cmp_le_i32_e64 s[10:11], v153, v192
	v_pk_mul_f32 v[152:153], v[102:103], s[36:37] op_sel_hi:[1,0]
	s_and_b64 vcc, vcc, s[8:9]
	v_cndmask_b32_e32 v197, v230, v153, vcc
	s_and_b64 vcc, s[0:1], s[10:11]
	v_cndmask_b32_e32 v198, v230, v152, vcc
	v_or_b32_e32 v152, 7, v138
	v_or_b32_e32 v153, 6, v138
	v_cmp_ge_i32_e32 vcc, v152, v141
	v_cmp_le_i32_e64 s[8:9], v152, v139
	v_cmp_ge_i32_e64 s[0:1], v153, v0
	v_cmp_le_i32_e64 s[10:11], v153, v192
	v_pk_mul_f32 v[152:153], v[104:105], s[36:37] op_sel_hi:[1,0]
	s_and_b64 vcc, vcc, s[8:9]
	v_cndmask_b32_e32 v199, v230, v153, vcc
	s_and_b64 vcc, s[0:1], s[10:11]
	v_cndmask_b32_e32 v200, v230, v152, vcc
	v_or_b32_e32 v152, 17, v138
	v_or_b32_e32 v153, 16, v138
	v_cmp_ge_i32_e32 vcc, v152, v141
	v_cmp_le_i32_e64 s[8:9], v152, v139
	v_cmp_ge_i32_e64 s[0:1], v153, v0
	v_cmp_le_i32_e64 s[10:11], v153, v192
	v_pk_mul_f32 v[152:153], v[106:107], s[36:37] op_sel_hi:[1,0]
	s_and_b64 vcc, vcc, s[8:9]
	v_cndmask_b32_e32 v209, v230, v153, vcc
	s_and_b64 vcc, s[0:1], s[10:11]
	v_cndmask_b32_e32 v210, v230, v152, vcc
	v_or_b32_e32 v152, 19, v138
	v_or_b32_e32 v153, 18, v138
	v_cmp_ge_i32_e32 vcc, v152, v141
	v_cmp_le_i32_e64 s[8:9], v152, v139
	v_cmp_ge_i32_e64 s[0:1], v153, v0
	v_cmp_le_i32_e64 s[10:11], v153, v192
	v_pk_mul_f32 v[152:153], v[108:109], s[36:37] op_sel_hi:[1,0]
	s_and_b64 vcc, vcc, s[8:9]
	v_cndmask_b32_e32 v211, v230, v153, vcc
	s_and_b64 vcc, s[0:1], s[10:11]
	v_cndmask_b32_e32 v212, v230, v152, vcc
	v_or_b32_e32 v152, 21, v138
	v_or_b32_e32 v153, 20, v138
	v_cmp_ge_i32_e32 vcc, v152, v141
	v_cmp_le_i32_e64 s[8:9], v152, v139
	v_max3_f32 v187, v157, s72, v167
	v_cmp_ge_i32_e64 s[0:1], v153, v0
	v_cmp_le_i32_e64 s[10:11], v153, v192
	v_pk_mul_f32 v[152:153], v[110:111], s[36:37] op_sel_hi:[1,0]
	s_and_b64 vcc, vcc, s[8:9]
	v_max3_f32 v187, v187, v196, v194
	v_cndmask_b32_e32 v213, v230, v153, vcc
	s_and_b64 vcc, s[0:1], s[10:11]
	v_max3_f32 v187, v187, v198, v197
	v_cndmask_b32_e32 v214, v230, v152, vcc
	v_or_b32_e32 v152, 23, v138
	v_max3_f32 v187, v187, v200, v199
	v_or_b32_e32 v138, 22, v138
	v_cmp_ge_i32_e32 vcc, v152, v141
	v_cmp_le_i32_e64 s[8:9], v152, v139
	v_max3_f32 v187, v187, v210, v209
	v_cmp_ge_i32_e64 s[0:1], v138, v0
	v_cmp_le_i32_e64 s[10:11], v138, v192
	v_pk_mul_f32 v[152:153], v[112:113], s[36:37] op_sel_hi:[1,0]
	s_and_b64 vcc, vcc, s[8:9]
	v_max3_f32 v187, v187, v212, v211
	v_cndmask_b32_e32 v138, v230, v153, vcc
	s_and_b64 vcc, s[0:1], s[10:11]
	v_max3_f32 v187, v187, v214, v213
	v_cndmask_b32_e32 v215, v230, v152, vcc
	v_max3_f32 v152, v187, v215, v138
	ds_bpermute_b32 v153, v193, v152
	v_cmp_lt_f32_e32 vcc, s62, v157
	s_waitcnt lgkmcnt(0)
	v_max3_f32 v152, v150, v152, v153
	v_sub_f32_e32 v153, v157, v152
	v_exp_f32_e32 v153, v153
	v_sub_f32_e32 v187, v167, v152
	v_exp_f32_e32 v187, v187
	v_sub_f32_e32 v216, v150, v152
	v_cndmask_b32_e32 v153, 0, v153, vcc
	v_cmp_lt_f32_e32 vcc, s62, v167
	v_add_f32_e32 v193, 0, v153
	s_nop 0
	v_cndmask_b32_e32 v157, 0, v187, vcc
	v_sub_f32_e32 v187, v194, v152
	v_add_f32_e32 v167, v157, v193
	v_exp_f32_e32 v187, v187
	v_sub_f32_e32 v193, v196, v152
	v_exp_f32_e32 v193, v193
	v_cmp_lt_f32_e32 vcc, s62, v194
	v_sub_f32_e32 v194, v197, v152
	v_exp_f32_e32 v194, v194
	v_cndmask_b32_e32 v187, 0, v187, vcc
	v_cmp_lt_f32_e32 vcc, s62, v196
	v_sub_f32_e32 v196, v198, v152
	v_exp_f32_e32 v196, v196
	v_cndmask_b32_e32 v193, 0, v193, vcc
	v_cmp_lt_f32_e32 vcc, s62, v197
	v_sub_f32_e32 v197, v199, v152
	v_exp_f32_e32 v197, v197
	v_cndmask_b32_e32 v194, 0, v194, vcc
	v_cmp_lt_f32_e32 vcc, s62, v198
	v_sub_f32_e32 v198, v200, v152
	v_exp_f32_e32 v198, v198
	v_cndmask_b32_e32 v196, 0, v196, vcc
	v_cmp_lt_f32_e32 vcc, s62, v199
	v_sub_f32_e32 v199, v209, v152
	v_exp_f32_e32 v199, v199
	v_cndmask_b32_e32 v197, 0, v197, vcc
	v_cmp_lt_f32_e32 vcc, s62, v200
	v_sub_f32_e32 v200, v210, v152
	v_exp_f32_e32 v200, v200
	v_cndmask_b32_e32 v198, 0, v198, vcc
	v_cmp_lt_f32_e32 vcc, s62, v209
	v_sub_f32_e32 v209, v211, v152
	v_add_f32_e32 v167, v193, v167
	v_cndmask_b32_e32 v199, 0, v199, vcc
	v_cmp_lt_f32_e32 vcc, s62, v210
	v_exp_f32_e32 v209, v209
	v_sub_f32_e32 v210, v212, v152
	v_add_f32_e32 v167, v187, v167
	v_cndmask_b32_e32 v200, 0, v200, vcc
	v_exp_f32_e32 v210, v210
	v_cmp_lt_f32_e32 vcc, s62, v211
	v_sub_f32_e32 v211, v213, v152
	v_add_f32_e32 v167, v196, v167
	v_exp_f32_e32 v211, v211
	v_add_f32_e32 v167, v194, v167
	v_add_f32_e32 v167, v198, v167
	v_cndmask_b32_e32 v209, 0, v209, vcc
	v_cmp_lt_f32_e32 vcc, s62, v212
	v_sub_f32_e32 v212, v214, v152
	v_add_f32_e32 v167, v197, v167
	v_cndmask_b32_e32 v210, 0, v210, vcc
	v_exp_f32_e32 v212, v212
	v_cmp_lt_f32_e32 vcc, s62, v213
	v_sub_f32_e32 v213, v138, v152
	v_add_f32_e32 v167, v200, v167
	v_cndmask_b32_e32 v211, 0, v211, vcc
	v_cmp_lt_f32_e32 vcc, s62, v214
	v_exp_f32_e32 v213, v213
	v_sub_f32_e32 v214, v215, v152
	v_add_f32_e32 v167, v199, v167
	v_exp_f32_e32 v214, v214
	v_add_f32_e32 v167, v210, v167
	v_add_f32_e32 v167, v209, v167
	v_cndmask_b32_e32 v212, 0, v212, vcc
	v_cmp_lt_f32_e32 vcc, s62, v138
	v_add_f32_e32 v167, v212, v167
	v_exp_f32_e32 v138, v216
	v_cndmask_b32_e32 v213, 0, v213, vcc
	v_cmp_lt_f32_e32 vcc, s62, v215
	v_add_f32_e32 v167, v211, v167
	s_nop 0
	v_cndmask_b32_e32 v214, 0, v214, vcc
	v_add_f32_e32 v167, v214, v167
	v_add_f32_e32 v167, v213, v167
	s_cbranch_execz .LBB0_395

.LBB0_384:
	s_nop 1
	v_add_u32_e32 v110, v149, v170
	s_nop 3
	ds_read_b128 v[98:101], v110 offset:9216
	ds_read_b128 v[238:241], v110 offset:9248
	ds_read_b128 v[242:245], v110 offset:13824
	ds_read_b128 v[246:249], v110 offset:13856
	v_cvt_pk_bf16_f32 v102, v153, v157
	v_cvt_pk_bf16_f32 v103, v193, v187
	v_cvt_pk_bf16_f32 v104, v196, v194
	v_cvt_pk_bf16_f32 v105, v198, v197
	v_cvt_pk_bf16_f32 v106, v200, v199
	v_cvt_pk_bf16_f32 v107, v210, v209
	v_cvt_pk_bf16_f32 v108, v212, v211
	v_cvt_pk_bf16_f32 v109, v214, v213
	s_waitcnt lgkmcnt(3)
	v_mfma_f32_32x32x16_bf16 v[82:97], v[98:101], v[102:105], v[82:97]
	v_fmac_f32_e32 v167, v147, v138
	v_mov_b32_e32 v147, v167
	v_mov_b32_e32 v150, v152
	s_waitcnt lgkmcnt(2)
	v_mfma_f32_32x32x16_bf16 v[82:97], v[238:241], v[106:109], v[82:97]
	s_waitcnt lgkmcnt(1)
	v_mfma_f32_32x32x16_bf16 v[66:81], v[242:245], v[102:105], v[66:81]
	s_waitcnt lgkmcnt(0)
	v_mfma_f32_32x32x16_bf16 v[66:81], v[246:249], v[106:109], v[66:81]
.LBB0_385:
	s_or_b32 s8, s26, 32
	s_cmp_gt_i32 s8, s61
	s_cbranch_scc1 .LBB0_392
	s_or_b32 s0, s26, 63
	s_cmp_lt_i32 s0, s18
	s_cbranch_scc1 .LBB0_392
	v_add_u32_e32 v138, v151, v204
	ds_read_b128 v[98:101], v138 offset:4608
	ds_read_b128 v[196:199], v138 offset:4640
	ds_read_b128 v[238:241], v138 offset:4672
	ds_read_b128 v[242:245], v138 offset:4704
	s_cmp_ge_i32 s8, s19
	s_cselect_b64 s[10:11], -1, 0
	s_cmp_le_i32 s0, s91
	s_cselect_b64 s[0:1], -1, 0
	s_and_b64 s[10:11], s[10:11], s[0:1]
	s_mov_b64 s[0:1], -1
	s_and_b64 vcc, exec, s[10:11]
	s_waitcnt lgkmcnt(2)
	v_mfma_f32_32x32x16_bf16 v[98:113], v[98:101], v[114:117], 0
	v_mfma_f32_32x32x16_bf16 v[98:113], v[196:199], v[118:121], v[98:113]
	s_waitcnt lgkmcnt(1)
	v_mfma_f32_32x32x16_bf16 v[98:113], v[238:241], v[126:129], v[98:113]
	s_waitcnt lgkmcnt(0)
	v_mfma_f32_32x32x16_bf16 v[98:113], v[242:245], v[122:125], v[98:113]
	s_cbranch_vccnz .LBB0_397
	v_or_b32_e32 v138, s8, v202
	v_cmp_ge_i32_e32 vcc, v138, v0
	v_cmp_le_i32_e64 s[0:1], v138, v192
	s_nop 7
	v_mul_f32_e32 v151, 0x3e38aa3b, v98
	s_and_b64 vcc, vcc, s[0:1]
	v_mov_b32_e32 v152, v222
	v_cndmask_b32_e32 v157, v230, v151, vcc
	v_or_b32_e32 v151, 1, v138
	v_cmp_ge_i32_e32 vcc, v151, v0
	v_cmp_lt_i32_e64 s[0:1], v138, v192
	v_lshlrev_b32_e32 v152, 2, v152
	v_mul_f32_e32 v151, 0x3e38aa3b, v99
	s_and_b64 vcc, s[0:1], vcc
	v_xor_b32_e32 v187, 0x80, v152
	v_or_b32_e32 v152, 3, v138
	v_cndmask_b32_e32 v167, v230, v151, vcc
	v_or_b32_e32 v153, 2, v138
	v_cmp_ge_i32_e32 vcc, v152, v141
	v_cmp_le_i32_e64 s[8:9], v152, v139
	v_cmp_ge_i32_e64 s[0:1], v153, v0
	v_cmp_le_i32_e64 s[10:11], v153, v192
	v_pk_mul_f32 v[152:153], v[100:101], s[36:37] op_sel_hi:[1,0]
	s_and_b64 vcc, vcc, s[8:9]
	v_cndmask_b32_e32 v193, v230, v153, vcc
	s_and_b64 vcc, s[0:1], s[10:11]
	v_cndmask_b32_e32 v194, v230, v152, vcc
	v_or_b32_e32 v152, 5, v138
	v_or_b32_e32 v153, 4, v138
	v_cmp_ge_i32_e32 vcc, v152, v141
	v_cmp_le_i32_e64 s[8:9], v152, v139
	v_cmp_ge_i32_e64 s[0:1], v153, v0
	v_cmp_le_i32_e64 s[10:11], v153, v192
	v_pk_mul_f32 v[152:153], v[102:103], s[36:37] op_sel_hi:[1,0]
	s_and_b64 vcc, vcc, s[8:9]
	v_cndmask_b32_e32 v196, v230, v153, vcc
	s_and_b64 vcc, s[0:1], s[10:11]
	v_cndmask_b32_e32 v197, v230, v152, vcc
	v_or_b32_e32 v152, 7, v138
	v_or_b32_e32 v153, 6, v138
	v_cmp_ge_i32_e32 vcc, v152, v141
	v_cmp_le_i32_e64 s[8:9], v152, v139
	v_cmp_ge_i32_e64 s[0:1], v153, v0
	v_cmp_le_i32_e64 s[10:11], v153, v192
	v_pk_mul_f32 v[152:153], v[104:105], s[36:37] op_sel_hi:[1,0]
	s_and_b64 vcc, vcc, s[8:9]
	v_cndmask_b32_e32 v198, v230, v153, vcc
	s_and_b64 vcc, s[0:1], s[10:11]
	v_cndmask_b32_e32 v199, v230, v152, vcc
	v_or_b32_e32 v152, 17, v138
	v_or_b32_e32 v153, 16, v138
	v_cmp_ge_i32_e32 vcc, v152, v141
	v_cmp_le_i32_e64 s[8:9], v152, v139
	v_cmp_ge_i32_e64 s[0:1], v153, v0
	v_cmp_le_i32_e64 s[10:11], v153, v192
	v_pk_mul_f32 v[152:153], v[106:107], s[36:37] op_sel_hi:[1,0]
	s_and_b64 vcc, vcc, s[8:9]
	v_cndmask_b32_e32 v200, v230, v153, vcc
	s_and_b64 vcc, s[0:1], s[10:11]
	v_cndmask_b32_e32 v209, v230, v152, vcc
	v_or_b32_e32 v152, 19, v138
	v_or_b32_e32 v153, 18, v138
	v_cmp_ge_i32_e32 vcc, v152, v141
	v_cmp_le_i32_e64 s[8:9], v152, v139
	v_cmp_ge_i32_e64 s[0:1], v153, v0
	v_cmp_le_i32_e64 s[10:11], v153, v192
	v_pk_mul_f32 v[152:153], v[108:109], s[36:37] op_sel_hi:[1,0]
	s_and_b64 vcc, vcc, s[8:9]
	v_cndmask_b32_e32 v210, v230, v153, vcc
	s_and_b64 vcc, s[0:1], s[10:11]
	v_cndmask_b32_e32 v211, v230, v152, vcc
	v_or_b32_e32 v152, 21, v138
	v_or_b32_e32 v153, 20, v138
	v_cmp_ge_i32_e32 vcc, v152, v141
	v_cmp_le_i32_e64 s[8:9], v152, v139
	v_max3_f32 v151, v157, s72, v167
	v_cmp_ge_i32_e64 s[0:1], v153, v0
	v_cmp_le_i32_e64 s[10:11], v153, v192
	v_pk_mul_f32 v[152:153], v[110:111], s[36:37] op_sel_hi:[1,0]
	s_and_b64 vcc, vcc, s[8:9]
	v_max3_f32 v151, v151, v194, v193
	v_cndmask_b32_e32 v212, v230, v153, vcc
	s_and_b64 vcc, s[0:1], s[10:11]
	v_max3_f32 v151, v151, v197, v196
	v_cndmask_b32_e32 v213, v230, v152, vcc
	v_or_b32_e32 v152, 23, v138
	v_max3_f32 v151, v151, v199, v198
	v_or_b32_e32 v138, 22, v138
	v_cmp_ge_i32_e32 vcc, v152, v141
	v_cmp_le_i32_e64 s[8:9], v152, v139
	v_max3_f32 v151, v151, v209, v200
	v_cmp_ge_i32_e64 s[0:1], v138, v0
	v_cmp_le_i32_e64 s[10:11], v138, v192
	v_pk_mul_f32 v[152:153], v[112:113], s[36:37] op_sel_hi:[1,0]
	s_and_b64 vcc, vcc, s[8:9]
	v_max3_f32 v151, v151, v211, v210
	v_cndmask_b32_e32 v138, v230, v153, vcc
	s_and_b64 vcc, s[0:1], s[10:11]
	v_max3_f32 v151, v151, v213, v212
	v_cndmask_b32_e32 v214, v230, v152, vcc
	v_max3_f32 v151, v151, v214, v138
	ds_bpermute_b32 v152, v187, v151
	v_cmp_lt_f32_e32 vcc, s62, v157
	s_waitcnt lgkmcnt(0)
	v_max3_f32 v151, v150, v151, v152
	v_sub_f32_e32 v152, v157, v151
	v_exp_f32_e32 v152, v152
	v_sub_f32_e32 v153, v167, v151
	v_exp_f32_e32 v153, v153
	v_sub_f32_e32 v187, v194, v151
	v_cndmask_b32_e32 v152, 0, v152, vcc
	v_cmp_lt_f32_e32 vcc, s62, v167
	v_sub_f32_e32 v167, v193, v151
	v_exp_f32_e32 v167, v167
	v_exp_f32_e32 v187, v187
	v_cndmask_b32_e32 v153, 0, v153, vcc
	v_cmp_lt_f32_e32 vcc, s62, v193
	v_sub_f32_e32 v193, v196, v151
	v_exp_f32_e32 v193, v193
	v_cndmask_b32_e32 v167, 0, v167, vcc
	v_cmp_lt_f32_e32 vcc, s62, v194
	v_sub_f32_e32 v194, v197, v151
	v_exp_f32_e32 v194, v194
	v_cndmask_b32_e32 v187, 0, v187, vcc
	v_cmp_lt_f32_e32 vcc, s62, v196
	v_sub_f32_e32 v196, v198, v151
	v_exp_f32_e32 v196, v196
	v_cndmask_b32_e32 v193, 0, v193, vcc
	v_cmp_lt_f32_e32 vcc, s62, v197
	v_sub_f32_e32 v197, v199, v151
	v_exp_f32_e32 v197, v197
	v_cndmask_b32_e32 v194, 0, v194, vcc
	v_cmp_lt_f32_e32 vcc, s62, v198
	v_sub_f32_e32 v198, v200, v151
	v_exp_f32_e32 v198, v198
	v_cndmask_b32_e32 v196, 0, v196, vcc
	v_cmp_lt_f32_e32 vcc, s62, v199
	v_sub_f32_e32 v199, v209, v151
	v_exp_f32_e32 v199, v199
	v_add_f32_e32 v157, 0, v152
	v_add_f32_e32 v157, v153, v157
	v_cndmask_b32_e32 v197, 0, v197, vcc
	v_cmp_lt_f32_e32 vcc, s62, v200
	v_sub_f32_e32 v200, v210, v151
	v_add_f32_e32 v157, v187, v157
	v_cndmask_b32_e32 v198, 0, v198, vcc
	v_cmp_lt_f32_e32 vcc, s62, v209
	v_exp_f32_e32 v200, v200
	v_sub_f32_e32 v209, v211, v151
	v_add_f32_e32 v157, v167, v157
	v_cndmask_b32_e32 v199, 0, v199, vcc
	v_exp_f32_e32 v209, v209
	v_cmp_lt_f32_e32 vcc, s62, v210
	v_sub_f32_e32 v210, v212, v151
	v_add_f32_e32 v157, v194, v157
	v_exp_f32_e32 v210, v210
	v_add_f32_e32 v157, v193, v157
	v_add_f32_e32 v157, v197, v157
	v_cndmask_b32_e32 v200, 0, v200, vcc
	v_cmp_lt_f32_e32 vcc, s62, v211
	v_sub_f32_e32 v211, v213, v151
	v_add_f32_e32 v157, v196, v157
	v_cndmask_b32_e32 v209, 0, v209, vcc
	v_exp_f32_e32 v211, v211
	v_cmp_lt_f32_e32 vcc, s62, v212
	v_sub_f32_e32 v212, v138, v151
	v_add_f32_e32 v157, v199, v157
	v_cndmask_b32_e32 v210, 0, v210, vcc
	v_cmp_lt_f32_e32 vcc, s62, v213
	v_exp_f32_e32 v212, v212
	v_sub_f32_e32 v213, v214, v151
	v_add_f32_e32 v157, v198, v157
	v_exp_f32_e32 v213, v213
	v_add_f32_e32 v157, v209, v157
	v_sub_f32_e32 v215, v150, v151
	v_add_f32_e32 v157, v200, v157
	v_cndmask_b32_e32 v211, 0, v211, vcc
	v_cmp_lt_f32_e32 vcc, s62, v138
	v_add_f32_e32 v157, v211, v157
	v_exp_f32_e32 v138, v215
	v_cndmask_b32_e32 v212, 0, v212, vcc
	v_cmp_lt_f32_e32 vcc, s62, v214
	v_add_f32_e32 v157, v210, v157
	s_nop 0
	v_cndmask_b32_e32 v213, 0, v213, vcc
	v_add_f32_e32 v157, v213, v157
	v_add_f32_e32 v157, v212, v157
	s_cbranch_execz .LBB0_398

.LBB0_391:
	s_nop 6
	v_add_u32_e32 v110, v149, v170
	ds_read_b128 v[98:101], v110 offset:9280
	ds_read_b128 v[238:241], v110 offset:9312
	ds_read_b128 v[242:245], v110 offset:13888
	ds_read_b128 v[246:249], v110 offset:13920
	v_cvt_pk_bf16_f32 v102, v152, v153
	v_cvt_pk_bf16_f32 v103, v187, v167
	v_cvt_pk_bf16_f32 v104, v194, v193
	v_cvt_pk_bf16_f32 v105, v197, v196
	v_cvt_pk_bf16_f32 v106, v199, v198
	v_cvt_pk_bf16_f32 v107, v209, v200
	v_cvt_pk_bf16_f32 v108, v211, v210
	v_cvt_pk_bf16_f32 v109, v213, v212
	s_waitcnt lgkmcnt(3)
	v_mfma_f32_32x32x16_bf16 v[82:97], v[98:101], v[102:105], v[82:97]
	v_fmac_f32_e32 v157, v147, v138
	v_mov_b32_e32 v147, v157
	v_mov_b32_e32 v150, v151
	s_waitcnt lgkmcnt(2)
	v_mfma_f32_32x32x16_bf16 v[82:97], v[238:241], v[106:109], v[82:97]
	s_waitcnt lgkmcnt(1)
	v_mfma_f32_32x32x16_bf16 v[66:81], v[242:245], v[102:105], v[66:81]
	s_waitcnt lgkmcnt(0)
	v_mfma_f32_32x32x16_bf16 v[66:81], v[246:249], v[106:109], v[66:81]
